# post_even loop software-pipelined (next trip loads before math, gn hoisted); final norm: g loads hoisted out of the row loop
# speedup vs baseline: 1.0095x; 1.0075x over previous
; __device__ __forceinline__ uint4 ld_nt16(const void* p) { const u32x4_t t = __builtin_nontemporal_load((const u32x4_t*)p); return make_uint4(t[0], t[1], t[2], t[3]); }
; __device__ void post_even_phase(int swave, const Params& p, int j) {
;     ...
;   for (int it = bidx * 32 + (tidx >> 4); it < TOK * 8; it += gridDim.x * 32) {
;     const int hh = it & 7, token = it >> 3;
;     const size_t oidx = (size_t)token * 1024 + hh * 128 + l16 * 8;
;     const uint4 a = ld_nt16(OF + oidx), bq = ld_nt16(OB + oidx);
;     const int gcol = (hh < 4 ? E_GR + hh * 128 : E_HG + (hh - 4) * 128) + l16 * 8;
;     const uint4 gt = ld_nt16(P + (size_t)token * EVEN_INP + gcol);
;     const float* gn = (hh < 4 ? gla_g + hh * 128 : hgrn_g + (hh - 4) * 128) + l16 * 8;
;     const float4 gn0 = *(const float4*)gn, gn1 = *(const float4*)(gn + 4);
;     const unsigned av[4] = {a.x, a.y, a.z, a.w}, bv[4] = {bq.x, bq.y, bq.z, bq.w}, gv[4] = {gt.x, gt.y, gt.z, gt.w};
.LBB0_68:
	s_andn2_b64 vcc, exec, s[0:1]
	s_cbranch_vccnz .LBB0_73
	v_mov_b32_e32 v0, v147
	s_mov_b32 s0, s85
	s_mov_b64 s[8:9], 0
	v_ashrrev_i32_e32 v1, 4, v0
	s_waitcnt vmcnt(0)
	v_lshl_add_u32 v6, s0, 5, v1
	s_mov_b32 s0, 0x40000
	s_mov_b64 s[2:3], 0
	s_mov_b64 s[4:5], 0
	s_mov_b64 s[6:7], 0
	s_mov_b64 s[10:11], 0
	s_mov_b64 s[12:13], 0
	v_cmp_gt_i32_e32 vcc, s0, v6
	s_and_saveexec_b64 s[0:1], vcc
	v_readlane_b32 s20, v247, 0
	s_cbranch_execz .LBB0_72
	v_readlane_b32 s16, v248, 8
	v_readlane_b32 s18, v248, 10
	v_readlane_b32 s19, v248, 11
	s_add_u32 s2, s18, s2
	s_addc_u32 s3, s19, s3
	s_add_u32 s2, s2, 0x4000000
	s_addc_u32 s3, s3, 0
	s_add_u32 s4, s18, s4
	s_addc_u32 s5, s19, s5
	s_add_u32 s4, s4, 0x8000000
	s_addc_u32 s5, s5, 0
	s_add_u32 s6, s18, s6
	v_readlane_b32 s68, v248, 28
	s_addc_u32 s7, s19, s7
	s_lshl_b64 s[12:13], s[12:13], 2
	v_readlane_b32 s72, v248, 32
	v_readlane_b32 s73, v248, 33
	s_add_u32 s14, s72, s12
	s_addc_u32 s15, s73, s13
	v_readlane_b32 s12, v247, 47
	v_readlane_b32 s17, v248, 9
	v_readlane_b32 s13, v247, 48
	s_mov_b32 s16, s12
	s_ashr_i32 s17, s12, 31
	v_writelane_b32 v247, s12, 47
	v_readlane_b32 s69, v248, 29
	v_bfe_u32 v4, v0, 4, 3
	v_writelane_b32 v247, s13, 48
	s_lshl_b64 s[12:13], s[16:17], 11
	s_add_u32 s14, s14, s12
	s_addc_u32 s15, s15, s13
	s_lshl_b64 s[10:11], s[10:11], 2
	s_add_u32 s10, s68, s10
	s_addc_u32 s11, s69, s11
	s_add_u32 s10, s10, s12
	v_lshlrev_b32_e32 v1, 3, v0
	v_lshlrev_b32_e32 v10, 7, v4
	s_addc_u32 s11, s11, s13
	v_and_b32_e32 v7, 0x78, v1
	v_or_b32_e32 v0, 0x400, v10
	v_add_u32_e32 v1, 0x920, v10
	v_cmp_gt_u32_e32 vcc, 4, v4
	s_add_u32 s8, s18, s8
	s_addc_u32 s9, s19, s9
	v_cndmask_b32_e32 v0, v1, v0, vcc
	v_add_lshl_u32 v2, v0, v7, 1
	v_lshl_add_u64 v[0:1], s[8:9], 0, v[2:3]
	s_mov_b64 s[8:9], 0xc000000
	v_lshl_add_u64 v[0:1], v[0:1], 0, s[8:9]
	v_lshlrev_b32_e32 v2, 9, v4
	s_movk_i32 s8, 0xf800
	v_lshl_add_u64 v[8:9], s[14:15], 0, v[2:3]
	s_mov_b32 s9, -1
	v_lshl_add_u64 v[4:5], s[10:11], 0, v[2:3]
	v_lshl_add_u64 v[8:9], v[8:9], 0, s[8:9]
	v_cndmask_b32_e32 v5, v9, v5, vcc
	v_cndmask_b32_e32 v4, v8, v4, vcc
	v_lshlrev_b32_e32 v2, 2, v7
	v_lshl_add_u64 v[4:5], v[4:5], 0, v[2:3]
	v_or_b32_e32 v2, v7, v10
	s_mov_b64 s[8:9], 0
	v_readlane_b32 s70, v248, 30
	v_readlane_b32 s71, v248, 31
	v_readlane_b32 s74, v248, 34
	v_readlane_b32 s75, v248, 35
	v_readlane_b32 s76, v248, 36
	v_readlane_b32 s77, v248, 37
	v_readlane_b32 s78, v248, 38
	v_readlane_b32 s79, v248, 39
	v_readlane_b32 s80, v248, 40
	v_readlane_b32 s81, v248, 41
	v_readlane_b32 s82, v248, 42
	v_readlane_b32 s83, v248, 43
	v_ashrrev_i32_e32 v16, 3, v6
	v_ashrrev_i32_e32 v17, 31, v16
	v_lshlrev_b64 v[28:29], 11, v[16:17]
	v_lshl_or_b32 v28, v2, 1, v28
	v_lshl_add_u64 v[8:9], s[2:3], 0, v[28:29]
	v_lshl_add_u64 v[12:13], s[4:5], 0, v[28:29]
	global_load_dwordx4 v[40:43], v[8:9], off nt
	v_mad_i64_i32 v[16:17], s[14:15], v16, s53, v[0:1]
	global_load_dwordx4 v[44:47], v[12:13], off nt
	s_nop 0
	global_load_dwordx4 v[48:51], v[16:17], off nt
	global_load_dwordx4 v[20:23], v[4:5], off offset:16
	global_load_dwordx4 v[24:27], v[4:5], off
	s_mov_b32 s10, 0x3ffff
	s_waitcnt vmcnt(0)
.LBB0_71:
	v_ashrrev_i32_e32 v16, 3, v6
	v_ashrrev_i32_e32 v17, 31, v16
	v_lshlrev_b64 v[28:29], 11, v[16:17]
	v_lshl_or_b32 v28, v2, 1, v28
	v_mov_b32_e32 v8, v40
	v_mov_b32_e32 v9, v41
	v_mov_b32_e32 v10, v42
	v_mov_b32_e32 v11, v43
	v_mov_b32_e32 v12, v44
	v_mov_b32_e32 v13, v45
	v_mov_b32_e32 v14, v46
	v_mov_b32_e32 v15, v47
	v_mov_b32_e32 v16, v48
	v_mov_b32_e32 v17, v49
	v_mov_b32_e32 v18, v50
	v_mov_b32_e32 v19, v51
	v_add_u32_e32 v6, s20, v6
	v_cmp_ge_i32_e32 vcc, s10, v6
	s_and_saveexec_b64 s[12:13], vcc
	s_cbranch_execz .Lpe_nopf
	v_ashrrev_i32_e32 v52, 3, v6
	v_ashrrev_i32_e32 v53, 31, v52
	v_lshlrev_b64 v[54:55], 11, v[52:53]
	v_lshl_or_b32 v54, v2, 1, v54
	v_lshl_add_u64 v[56:57], s[2:3], 0, v[54:55]
	v_lshl_add_u64 v[58:59], s[4:5], 0, v[54:55]
	global_load_dwordx4 v[40:43], v[56:57], off nt
	v_mad_i64_i32 v[52:53], s[14:15], v52, s53, v[0:1]
	global_load_dwordx4 v[44:47], v[58:59], off nt
	s_nop 0
	global_load_dwordx4 v[48:51], v[52:53], off nt
; __device__ __forceinline__ unsigned pk2(float lo, float hi) { f32x2_t v = {lo, hi}; bf16x2_t b = __builtin_convertvector(v, bf16x2_t); return __builtin_bit_cast(unsigned, b); }
; __device__ __forceinline__ float lo_bf(unsigned u) { return __uint_as_float(u << 16); }
; __device__ __forceinline__ float hi_bf(unsigned u) { return __uint_as_float(u & 0xffff0000u); }
; __device__ __forceinline__ float siluf_(float x) { return x * __builtin_amdgcn_rcpf(1.f + __expf(-x)); }
; __device__ void post_even_phase(int swave, const Params& p, int j) {
;     ...
;     const float gnv[8] = {gn0.x, gn0.y, gn0.z, gn0.w, gn1.x, gn1.y, gn1.z, gn1.w};
;     float o[8]; float ss = 0.f;
; #pragma unroll
;     for (int e = 0; e < 4; ++e) { o[2 * e] = lo_bf(av[e]) + lo_bf(bv[e]); o[2 * e + 1] = hi_bf(av[e]) + hi_bf(bv[e]); ss += o[2 * e] * o[2 * e] + o[2 * e + 1] * o[2 * e + 1]; }
;     ss = row16_allsum(ss);
;     const float rs = rsqrtf(ss * (1.f / 128.f) + EPS);
;     unsigned ov[4];
; #pragma unroll
;     for (int e = 0; e < 4; ++e)
;       ov[e] = pk2(o[2 * e] * rs * gnv[2 * e] * siluf_(lo_bf(gv[e])), o[2 * e + 1] * rs * gnv[2 * e + 1] * siluf_(hi_bf(gv[e])));
;     *(uint4*)(Y + oidx) = make_uint4(ov[0], ov[1], ov[2], ov[3]);
;   }
.Lpe_nopf:
	s_or_b64 exec, exec, s[12:13]
	v_lshlrev_b32_e32 v30, 16, v11
	v_and_b32_e32 v31, 0xffff0000, v11
	v_lshlrev_b32_e32 v32, 16, v15
	v_and_b32_e32 v33, 0xffff0000, v15
	v_pk_add_f32 v[30:31], v[30:31], v[32:33]
	v_lshlrev_b32_e32 v32, 16, v10
	v_and_b32_e32 v33, 0xffff0000, v10
	v_lshlrev_b32_e32 v10, 16, v14
	v_and_b32_e32 v11, 0xffff0000, v14
	v_pk_add_f32 v[10:11], v[32:33], v[10:11]
	v_mov_b32_e32 v32, v31
	v_mov_b32_e32 v33, v11
	v_mov_b32_e32 v14, v30
	v_mov_b32_e32 v15, v10
	v_pk_mul_f32 v[32:33], v[32:33], v[32:33]
	v_lshlrev_b32_e32 v36, 16, v13
	v_pk_fma_f32 v[14:15], v[14:15], v[14:15], v[32:33]
	v_lshlrev_b32_e32 v32, 16, v18
	v_mul_f32_e32 v7, 0xbfb8aa3b, v32
	v_exp_f32_e32 v7, v7
	v_and_b32_e32 v33, 0xffff0000, v18
	v_and_b32_e32 v37, 0xffff0000, v13
	v_add_f32_e32 v7, 1.0, v7
	v_rcp_f32_e32 v34, v7
	v_mul_f32_e32 v7, 0xbfb8aa3b, v33
	v_exp_f32_e32 v7, v7
	s_nop 0
	v_add_f32_e32 v7, 1.0, v7
	v_rcp_f32_e32 v35, v7
	s_nop 0
	v_pk_mul_f32 v[32:33], v[34:35], v[32:33]
	v_lshlrev_b32_e32 v34, 16, v9
	v_and_b32_e32 v35, 0xffff0000, v9
	v_pk_add_f32 v[34:35], v[34:35], v[36:37]
	v_lshlrev_b32_e32 v36, 16, v17
	v_mul_f32_e32 v7, 0xbfb8aa3b, v36
	v_exp_f32_e32 v7, v7
	v_and_b32_e32 v37, 0xffff0000, v17
	v_and_b32_e32 v9, 0xffff0000, v12
	v_mov_b32_e32 v13, v34
	v_add_f32_e32 v7, 1.0, v7
	v_rcp_f32_e32 v38, v7
	v_mul_f32_e32 v7, 0xbfb8aa3b, v37
	v_exp_f32_e32 v7, v7
	s_nop 0
	v_add_f32_e32 v7, 1.0, v7
	v_rcp_f32_e32 v39, v7
	s_nop 0
	v_pk_mul_f32 v[36:37], v[38:39], v[36:37]
	v_lshlrev_b32_e32 v38, 16, v8
	v_and_b32_e32 v39, 0xffff0000, v8
	v_lshlrev_b32_e32 v8, 16, v12
	v_pk_add_f32 v[8:9], v[38:39], v[8:9]
	v_mov_b32_e32 v39, v35
	v_mov_b32_e32 v38, v9
	v_mov_b32_e32 v12, v8
	v_pk_mul_f32 v[38:39], v[38:39], v[38:39]
	s_nop 0
	v_pk_fma_f32 v[12:13], v[12:13], v[12:13], v[38:39]
	v_lshlrev_b32_e32 v38, 16, v16
	v_mul_f32_e32 v7, 0xbfb8aa3b, v38
	v_exp_f32_e32 v7, v7
	v_and_b32_e32 v39, 0xffff0000, v16
	v_add_f32_e32 v7, 1.0, v7
	v_rcp_f32_e32 v16, v7
	v_mul_f32_e32 v7, 0xbfb8aa3b, v39
	v_exp_f32_e32 v7, v7
	s_nop 0
	v_add_f32_e32 v7, 1.0, v7
	v_rcp_f32_e32 v17, v7
	v_add_f32_e32 v7, v12, v13
	v_add_f32_e32 v7, v15, v7
	v_add_f32_e32 v7, v14, v7
	v_pk_mul_f32 v[16:17], v[16:17], v[38:39]
	s_nop 0
	v_add_f32_dpp v7, v7, v7 row_ror:8 row_mask:0xf bank_mask:0xf bound_ctrl:1
	s_nop 1
	v_add_f32_dpp v7, v7, v7 row_ror:4 row_mask:0xf bank_mask:0xf bound_ctrl:1
	s_nop 1
	v_add_f32_dpp v7, v7, v7 row_ror:2 row_mask:0xf bank_mask:0xf bound_ctrl:1
	s_nop 1
	v_add_f32_dpp v7, v7, v7 row_ror:1 row_mask:0xf bank_mask:0xf bound_ctrl:1
	v_fmamk_f32 v7, v7, 0x3c000000, v132
	v_cmp_gt_f32_e32 vcc, s26, v7
	v_mul_f32_e32 v12, 0x4b800000, v7
	s_nop 0
	v_cndmask_b32_e32 v7, v7, v12, vcc
	v_rsq_f32_e32 v7, v7
	s_nop 0
	v_mul_f32_e32 v12, 0x45800000, v7
	v_cndmask_b32_e32 v12, v7, v12, vcc
	v_pk_mul_f32 v[8:9], v[8:9], v[12:13] op_sel_hi:[1,0]
	v_pk_mul_f32 v[14:15], v[34:35], v[12:13] op_sel_hi:[1,0]
	v_pk_mul_f32 v[8:9], v[24:25], v[8:9]
	v_pk_mul_f32 v[14:15], v[26:27], v[14:15]
	v_pk_mul_f32 v[8:9], v[16:17], v[8:9]
	v_pk_mul_f32 v[14:15], v[36:37], v[14:15]
	v_cvt_pk_bf16_f32 v8, v8, v9
	v_cvt_pk_bf16_f32 v9, v14, v15
	v_lshlrev_b32_e32 v14, 16, v19
	v_mul_f32_e32 v7, 0xbfb8aa3b, v14
	v_exp_f32_e32 v7, v7
	v_and_b32_e32 v15, 0xffff0000, v19
	v_pk_mul_f32 v[10:11], v[10:11], v[12:13] op_sel_hi:[1,0]
	v_pk_mul_f32 v[12:13], v[30:31], v[12:13] op_sel_hi:[1,0]
	v_add_f32_e32 v7, 1.0, v7
	v_rcp_f32_e32 v16, v7
	v_mul_f32_e32 v7, 0xbfb8aa3b, v15
	v_exp_f32_e32 v7, v7
	v_pk_mul_f32 v[10:11], v[20:21], v[10:11]
	v_pk_mul_f32 v[12:13], v[22:23], v[12:13]
	v_pk_mul_f32 v[10:11], v[32:33], v[10:11]
	v_add_f32_e32 v7, 1.0, v7
	v_rcp_f32_e32 v17, v7
	v_cmp_lt_i32_e32 vcc, s10, v6
	v_cvt_pk_bf16_f32 v10, v10, v11
	s_or_b64 s[8:9], vcc, s[8:9]
	v_pk_mul_f32 v[14:15], v[16:17], v[14:15]
	s_nop 0
	v_pk_mul_f32 v[12:13], v[14:15], v[12:13]
	s_nop 0
	v_cvt_pk_bf16_f32 v11, v12, v13
	v_lshl_add_u64 v[12:13], s[6:7], 0, v[28:29]
	global_store_dwordx4 v[12:13], v[8:11], off
	s_waitcnt vmcnt(1)
	s_andn2_b64 exec, exec, s[8:9]
	s_cbranch_execnz .LBB0_71

; __device__ __forceinline__ int BIDX() { int t = blockIdx.x; asm volatile("" : "+s"(t)); return t; }
; __device__ __forceinline__ float4 ld_nt16f(const void* p) { const f32x4 t = __builtin_nontemporal_load((const f32x4*)p); return make_float4(t[0], t[1], t[2], t[3]); }
; __device__ __forceinline__ float lo_bf(unsigned u) { return __uint_as_float(u << 16); }
; __device__ __forceinline__ float hi_bf(unsigned u) { return __uint_as_float(u & 0xffff0000u); }
; __device__ __forceinline__ void final_norm(int swave, float* x, const bf16_t* add, const float* g) {
;   const int tidx = TIDX(swave);
;   const int bidx = BIDX();
;   const int wave = tidx >> 6, lane = tidx & 63;
;   for (int row = bidx * 8 + wave; row < TOK; row += gridDim.x * 8) {
;     float4* xr = (float4*)(x + (size_t)row * DM);
;     const uint2* ar = (const uint2*)(add + (size_t)row * DM);
;     float4 v[4]; float ss = 0.f;
; #pragma unroll
;     for (int u = 0; u < 4; ++u) {
;       v[u] = ld_nt16f(xr + lane + 64 * u); const uint2 a2 = ar[lane + 64 * u];
;       v[u].x += lo_bf(a2.x); v[u].y += hi_bf(a2.x); v[u].z += lo_bf(a2.y); v[u].w += hi_bf(a2.y);
;       ss += v[u].x * v[u].x + v[u].y * v[u].y + v[u].z * v[u].z + v[u].w * v[u].w;
;     }
;     ss = wave_sum(ss, lane);
;     const float r = rsqrtf(ss * (1.f / DM) + EPS);
; #pragma unroll
;     for (int u = 0; u < 4; ++u) {
;       float4 gg = ((const float4*)g)[lane + 64 * u];
;       { const f32x4 t = {v[u].x * r * gg.x, v[u].y * r * gg.y, v[u].z * r * gg.z, v[u].w * r * gg.w}; __builtin_nontemporal_store(t, (f32x4*)xr + lane + 64 * u); }
;     }
;   }
.LBB0_894:
	s_andn2_b64 vcc, exec, s[0:1]
	v_readlane_b32 s12, v247, 46
	s_cbranch_vccnz .Ltramp_24
	s_mov_b64 s[2:3], 0
	s_mov_b64 s[6:7], 0
	s_mov_b64 s[4:5], 0
	v_mov_b32_e32 v1, v147
	s_mov_b32 s0, s85
	s_nop 0
	v_ashrrev_i32_e32 v0, 6, v1
	v_lshl_add_u32 v0, s0, 3, v0
	s_mov_b32 s0, 0x8000
	v_cmp_gt_i32_e32 vcc, s0, v0
	s_and_saveexec_b64 s[0:1], vcc
	s_cbranch_execz .Ltramp_23
	v_readlane_b32 s8, v248, 8
	v_readlane_b32 s10, v248, 10
	v_readlane_b32 s11, v248, 11
	s_add_u32 s6, s10, s6
	v_readlane_b32 s36, v248, 12
	s_addc_u32 s7, s11, s7
	s_lshl_b64 s[4:5], s[4:5], 2
	v_readlane_b32 s42, v248, 18
	v_readlane_b32 s43, v248, 19
	s_add_u32 s4, s42, s4
	s_addc_u32 s5, s43, s5
	s_lshl_b64 s[2:3], s[2:3], 2
	v_and_b32_e32 v1, 63, v1
	v_readlane_b32 s9, v248, 9
	s_add_u32 s2, s8, s2
	v_lshlrev_b32_e32 v2, 2, v1
	s_addc_u32 s3, s9, s3
	s_waitcnt vmcnt(0)
	v_xor_b32_e32 v10, 0x80, v2
	v_xor_b32_e32 v11, 64, v2
	v_xor_b32_e32 v12, 32, v2
	v_xor_b32_e32 v13, 16, v2
	v_xor_b32_e32 v14, 8, v2
	v_xor_b32_e32 v15, 4, v2
	v_lshlrev_b32_e32 v2, 4, v1
	v_lshl_add_u64 v[4:5], s[4:5], 0, v[2:3]
	v_lshl_add_u64 v[6:7], s[2:3], 0, v[2:3]
	v_lshlrev_b32_e32 v2, 3, v1
	v_lshl_add_u64 v[8:9], s[6:7], 0, v[2:3]
	s_mov_b64 s[2:3], 0xc000000
	v_lshl_add_u64 v[8:9], v[8:9], 0, s[2:3]
	s_mov_b64 s[2:3], 0
	v_readlane_b32 s37, v248, 13
	v_readlane_b32 s38, v248, 14
	v_readlane_b32 s39, v248, 15
	v_readlane_b32 s40, v248, 16
	v_readlane_b32 s41, v248, 17
	v_readlane_b32 s44, v248, 20
	v_readlane_b32 s45, v248, 21
	v_readlane_b32 s46, v248, 22
	v_readlane_b32 s47, v248, 23
	v_readlane_b32 s48, v248, 24
	v_readlane_b32 s49, v248, 25
	v_readlane_b32 s50, v248, 26
	v_readlane_b32 s51, v248, 27
	global_load_dwordx4 v[60:63], v[4:5], off
	global_load_dwordx4 v[64:67], v[4:5], off offset:1024
	global_load_dwordx4 v[68:71], v[4:5], off offset:2048
	global_load_dwordx4 v[72:75], v[4:5], off offset:3072
.LBB0_897:
	v_ashrrev_i32_e32 v1, 31, v0
	v_lshlrev_b64 v[16:17], 11, v[0:1]
	v_lshl_add_u64 v[16:17], v[8:9], 0, v[16:17]
	global_load_dwordx2 v[36:37], v[16:17], off
	global_load_dwordx2 v[38:39], v[16:17], off offset:512
	global_load_dwordx2 v[40:41], v[16:17], off offset:1024
	global_load_dwordx2 v[42:43], v[16:17], off offset:1536
	v_lshlrev_b64 v[16:17], 12, v[0:1]
	v_lshl_add_u64 v[44:45], v[6:7], 0, v[16:17]
	global_load_dwordx4 v[16:19], v[44:45], off nt
	global_load_dwordx4 v[20:23], v[44:45], off offset:1024 nt
	global_load_dwordx4 v[24:27], v[44:45], off offset:2048 nt
	global_load_dwordx4 v[28:31], v[44:45], off offset:3072 nt
	v_add_u32_e32 v0, s84, v0
	s_waitcnt vmcnt(0)
	v_lshlrev_b32_e32 v46, 16, v36
	v_and_b32_e32 v47, 0xffff0000, v36
	v_lshlrev_b32_e32 v48, 16, v38
	v_and_b32_e32 v49, 0xffff0000, v38
	v_lshlrev_b32_e32 v38, 16, v39
	v_and_b32_e32 v39, 0xffff0000, v39
	v_lshlrev_b32_e32 v50, 16, v40
	v_and_b32_e32 v51, 0xffff0000, v40
	v_lshlrev_b32_e32 v52, 16, v42
	v_and_b32_e32 v53, 0xffff0000, v42
	v_pk_add_f32 v[16:17], v[16:17], v[46:47]
	v_pk_add_f32 v[20:21], v[20:21], v[48:49]
	v_lshlrev_b32_e32 v36, 16, v37
	v_and_b32_e32 v37, 0xffff0000, v37
	v_pk_add_f32 v[22:23], v[22:23], v[38:39]
	v_pk_add_f32 v[24:25], v[24:25], v[50:51]
	v_pk_add_f32 v[28:29], v[28:29], v[52:53]
	v_mov_b32_e32 v38, v17
	v_mov_b32_e32 v39, v21
	v_lshlrev_b32_e32 v40, 16, v41
	v_and_b32_e32 v41, 0xffff0000, v41
	v_lshlrev_b32_e32 v42, 16, v43
	v_and_b32_e32 v43, 0xffff0000, v43
	v_pk_add_f32 v[18:19], v[18:19], v[36:37]
	v_mov_b32_e32 v36, v16
	v_mov_b32_e32 v37, v20
	v_mov_b32_e32 v48, v25
	v_mov_b32_e32 v49, v29
	v_pk_mul_f32 v[38:39], v[38:39], v[38:39]
	v_pk_add_f32 v[26:27], v[26:27], v[40:41]
	v_pk_add_f32 v[30:31], v[30:31], v[42:43]
	v_mov_b32_e32 v40, v18
	v_mov_b32_e32 v41, v22
	v_mov_b32_e32 v46, v24
	v_mov_b32_e32 v47, v28
	v_pk_mul_f32 v[48:49], v[48:49], v[48:49]
	v_pk_fma_f32 v[36:37], v[36:37], v[36:37], v[38:39]
	v_mov_b32_e32 v42, v19
	v_mov_b32_e32 v43, v23
	v_mov_b32_e32 v50, v26
	v_mov_b32_e32 v51, v30
	v_pk_fma_f32 v[38:39], v[46:47], v[46:47], v[48:49]
	v_pk_fma_f32 v[36:37], v[40:41], v[40:41], v[36:37]
	v_mov_b32_e32 v52, v27
	v_mov_b32_e32 v53, v31
	v_pk_fma_f32 v[38:39], v[50:51], v[50:51], v[38:39]
	v_pk_fma_f32 v[36:37], v[42:43], v[42:43], v[36:37]
	v_pk_fma_f32 v[38:39], v[52:53], v[52:53], v[38:39]
	v_add_f32_e32 v1, v36, v37
	v_add_f32_e32 v1, v1, v38
	v_add_f32_e32 v1, v1, v39
	ds_bpermute_b32 v2, v10, v1
	s_waitcnt lgkmcnt(0)
	v_add_f32_e32 v1, v1, v2
	ds_bpermute_b32 v2, v11, v1
	s_waitcnt lgkmcnt(0)
	v_add_f32_e32 v1, v1, v2
	ds_bpermute_b32 v2, v12, v1
	s_waitcnt lgkmcnt(0)
	v_add_f32_e32 v1, v1, v2
	ds_bpermute_b32 v2, v13, v1
	s_waitcnt lgkmcnt(0)
	v_add_f32_e32 v1, v1, v2
	ds_bpermute_b32 v2, v14, v1
	s_waitcnt lgkmcnt(0)
	v_add_f32_e32 v1, v1, v2
	ds_bpermute_b32 v2, v15, v1
	s_waitcnt lgkmcnt(0)
	v_add_f32_e32 v1, v1, v2
	v_fmamk_f32 v1, v1, 0x3a800000, v132
	v_mul_f32_e32 v2, 0x4b800000, v1
	v_cmp_gt_f32_e32 vcc, s26, v1
	s_nop 1
	v_cndmask_b32_e32 v1, v1, v2, vcc
	v_rsq_f32_e32 v1, v1
	s_nop 0
	v_mul_f32_e32 v2, 0x45800000, v1
	v_cndmask_b32_e32 v2, v1, v2, vcc
	v_pk_mul_f32 v[16:17], v[16:17], v[2:3] op_sel_hi:[1,0]
	v_pk_mul_f32 v[18:19], v[18:19], v[2:3] op_sel_hi:[1,0]
	v_pk_mul_f32 v[16:17], v[60:61], v[16:17]
	v_pk_mul_f32 v[18:19], v[62:63], v[18:19]
	global_store_dwordx4 v[44:45], v[16:19], off nt
	v_pk_mul_f32 v[22:23], v[22:23], v[2:3] op_sel_hi:[1,0]
	v_pk_mul_f32 v[20:21], v[20:21], v[2:3] op_sel_hi:[1,0]
	v_cmp_lt_i32_e32 vcc, s97, v0
	s_or_b64 s[2:3], vcc, s[2:3]
	v_pk_mul_f32 v[16:17], v[64:65], v[20:21]
	v_pk_mul_f32 v[18:19], v[66:67], v[22:23]
	global_store_dwordx4 v[44:45], v[16:19], off offset:1024 nt
	v_pk_mul_f32 v[20:21], v[26:27], v[2:3] op_sel_hi:[1,0]
	v_pk_mul_f32 v[22:23], v[24:25], v[2:3] op_sel_hi:[1,0]
	v_pk_mul_f32 v[18:19], v[70:71], v[20:21]
	v_pk_mul_f32 v[16:17], v[68:69], v[22:23]
	global_store_dwordx4 v[44:45], v[16:19], off offset:2048 nt
	v_pk_mul_f32 v[20:21], v[30:31], v[2:3] op_sel_hi:[1,0]
	v_pk_mul_f32 v[22:23], v[28:29], v[2:3] op_sel_hi:[1,0]
	v_pk_mul_f32 v[18:19], v[20:21], v[74:75]
	v_pk_mul_f32 v[16:17], v[22:23], v[72:73]
	global_store_dwordx4 v[44:45], v[16:19], off offset:3072 nt
	s_andn2_b64 exec, exec, s[2:3]
	s_cbranch_execnz .LBB0_897
	s_branch .Ltramp_23
